# P1 GEMM: first K iteration peeled with C=0 on first-touch MFMAs, accumulator zeroing deleted
# baseline (speedup 1.0000x reference)
.LBB0_168:
	s_ashr_i32 s25, s24, 31
	s_lshl_b64 s[42:43], s[24:25], 19
	s_add_u32 s42, s48, s42
	s_addc_u32 s43, s49, s43
	s_and_b64 s[44:45], s[4:5], exec
	s_cselect_b32 s7, s43, s55
	s_cselect_b32 s9, s42, s54
	s_ashr_i32 s23, s22, 31
	s_lshl_b64 s[44:45], s[22:23], 19
	s_add_u32 s44, s21, s44
	s_addc_u32 s45, s80, s45
	s_and_b64 s[70:71], s[4:5], exec
	s_cselect_b32 s23, s45, s57
	s_cselect_b32 s25, s44, s56
	s_add_u32 s54, s54, 0x40080
	s_addc_u32 s55, s55, 0
	s_add_u32 s72, s56, 0x100
	s_addc_u32 s73, s57, 0
	s_mov_b32 s74, -2
	s_waitcnt lgkmcnt(0)
	ds_read_b128 v[146:149], v157
	ds_read_b128 v[150:153], v157 offset:1024
	ds_read_b128 v[162:165], v157 offset:2048
	ds_read_b128 v[166:169], v157 offset:3072
	ds_read_b128 v[170:173], v158
	ds_read_b128 v[174:177], v158 offset:1024
	ds_read_b128 v[178:181], v158 offset:2048
	ds_read_b128 v[182:185], v158 offset:3072
	s_add_u32 s56, s54, 0xfffc0080
	s_addc_u32 s57, s55, -1
	s_cmp_eq_u32 s74, 12
	s_cselect_b32 s71, s7, s57
	s_cselect_b32 s70, s9, s56
	s_cselect_b32 s57, s23, s73
	s_cselect_b32 s56, s25, s72
	v_lshl_add_u64 v[218:219], s[54:55], 0, v[138:139]
	s_add_i32 m0, s82, 0xc000
	ds_read_b128 v[186:189], v159
	ds_read_b128 v[190:193], v159 offset:1024
	ds_read_b128 v[194:197], v159 offset:2048
	ds_read_b128 v[198:201], v159 offset:3072
	ds_read_b128 v[202:205], v159 offset:4096
	ds_read_b128 v[206:209], v159 offset:5120
	ds_read_b128 v[210:213], v159 offset:6144
	ds_read_b128 v[214:217], v159 offset:7168
	global_load_lds_dwordx4 v[218:219], off
	v_lshl_add_u64 v[218:219], s[54:55], 0, v[140:141]
	s_add_i32 m0, s82, 0xe000
	s_nop 0
	global_load_lds_dwordx4 v[218:219], off
	s_waitcnt vmcnt(8)
	s_waitcnt lgkmcnt(0)
	s_barrier
	s_setprio 1
	s_waitcnt lgkmcnt(0)
	v_mfma_f32_16x16x32_bf16 v[126:129], v[146:149], v[186:189], 0
	v_mfma_f32_16x16x32_bf16 v[122:125], v[162:165], v[186:189], 0
	v_mfma_f32_16x16x32_bf16 v[110:113], v[146:149], v[194:197], 0
	v_mfma_f32_16x16x32_bf16 v[106:109], v[162:165], v[194:197], 0
	v_mfma_f32_16x16x32_bf16 v[94:97], v[146:149], v[202:205], 0
	v_mfma_f32_16x16x32_bf16 v[90:93], v[162:165], v[202:205], 0
	v_mfma_f32_16x16x32_bf16 v[78:81], v[146:149], v[210:213], 0
	v_mfma_f32_16x16x32_bf16 v[74:77], v[162:165], v[210:213], 0
	v_mfma_f32_16x16x32_bf16 v[126:129], v[150:153], v[190:193], v[126:129]
	v_mfma_f32_16x16x32_bf16 v[122:125], v[166:169], v[190:193], v[122:125]
	v_mfma_f32_16x16x32_bf16 v[110:113], v[150:153], v[198:201], v[110:113]
	v_mfma_f32_16x16x32_bf16 v[106:109], v[166:169], v[198:201], v[106:109]
	v_mfma_f32_16x16x32_bf16 v[94:97], v[150:153], v[206:209], v[94:97]
	v_mfma_f32_16x16x32_bf16 v[90:93], v[166:169], v[206:209], v[90:93]
	v_mfma_f32_16x16x32_bf16 v[78:81], v[150:153], v[214:217], v[78:81]
	v_mfma_f32_16x16x32_bf16 v[74:77], v[166:169], v[214:217], v[74:77]
	s_setprio 0
	s_setprio 1
	v_mfma_f32_16x16x32_bf16 v[118:121], v[170:173], v[186:189], 0
	v_mfma_f32_16x16x32_bf16 v[114:117], v[178:181], v[186:189], 0
	v_mfma_f32_16x16x32_bf16 v[102:105], v[170:173], v[194:197], 0
	v_mfma_f32_16x16x32_bf16 v[98:101], v[178:181], v[194:197], 0
	v_mfma_f32_16x16x32_bf16 v[86:89], v[170:173], v[202:205], 0
	v_mfma_f32_16x16x32_bf16 v[82:85], v[178:181], v[202:205], 0
	v_mfma_f32_16x16x32_bf16 v[70:73], v[170:173], v[210:213], 0
	v_mfma_f32_16x16x32_bf16 v[66:69], v[178:181], v[210:213], 0
	v_mfma_f32_16x16x32_bf16 v[118:121], v[174:177], v[190:193], v[118:121]
	v_mfma_f32_16x16x32_bf16 v[114:117], v[182:185], v[190:193], v[114:117]
	v_mfma_f32_16x16x32_bf16 v[102:105], v[174:177], v[198:201], v[102:105]
	v_mfma_f32_16x16x32_bf16 v[98:101], v[182:185], v[198:201], v[98:101]
	v_mfma_f32_16x16x32_bf16 v[86:89], v[174:177], v[206:209], v[86:89]
	v_mfma_f32_16x16x32_bf16 v[82:85], v[182:185], v[206:209], v[82:85]
	v_mfma_f32_16x16x32_bf16 v[70:73], v[174:177], v[214:217], v[70:73]
	v_mfma_f32_16x16x32_bf16 v[66:69], v[182:185], v[214:217], v[66:69]
	s_setprio 0
	s_barrier
	s_add_i32 s75, s93, s81
	v_lshl_add_u64 v[218:219], s[56:57], 0, v[132:133]
	s_mov_b32 m0, s75
	ds_read_b128 v[186:189], v159 offset:16384
	ds_read_b128 v[190:193], v159 offset:17408
	ds_read_b128 v[194:197], v159 offset:18432
	ds_read_b128 v[198:201], v159 offset:19456
	ds_read_b128 v[202:205], v159 offset:20480
	ds_read_b128 v[206:209], v159 offset:21504
	ds_read_b128 v[210:213], v159 offset:22528
	ds_read_b128 v[214:217], v159 offset:23552
	global_load_lds_dwordx4 v[218:219], off
	s_add_i32 m0, s75, 0x2000
	s_add_u32 s76, s56, 0x40000
	v_lshl_add_u64 v[220:221], s[56:57], 0, v[136:137]
	s_addc_u32 s77, s57, 0
	s_add_i32 s75, s94, s81
	global_load_lds_dwordx4 v[220:221], off
	v_lshl_add_u64 v[222:223], s[76:77], 0, v[132:133]
	s_mov_b32 m0, s75
	v_lshl_add_u64 v[224:225], s[70:71], 0, v[134:135]
	global_load_lds_dwordx4 v[222:223], off
	v_lshl_add_u64 v[222:223], s[76:77], 0, v[136:137]
	s_add_i32 m0, s75, 0x2000
	s_nop 0
	global_load_lds_dwordx4 v[222:223], off
	v_lshl_add_u64 v[222:223], s[70:71], 0, v[130:131]
	s_mov_b32 m0, s82
	s_nop 0
	global_load_lds_dwordx4 v[222:223], off
	s_mov_b32 m0, s83
	s_nop 0
	global_load_lds_dwordx4 v[224:225], off
	s_waitcnt vmcnt(8)
	s_waitcnt lgkmcnt(0)
	s_barrier
	s_setprio 1
	s_waitcnt lgkmcnt(0)
	v_mfma_f32_16x16x32_bf16 v[62:65], v[146:149], v[186:189], 0
	v_mfma_f32_16x16x32_bf16 v[58:61], v[162:165], v[186:189], 0
	v_mfma_f32_16x16x32_bf16 v[46:49], v[146:149], v[194:197], 0
	v_mfma_f32_16x16x32_bf16 v[42:45], v[162:165], v[194:197], 0
	v_mfma_f32_16x16x32_bf16 v[30:33], v[146:149], v[202:205], 0
	v_mfma_f32_16x16x32_bf16 v[26:29], v[162:165], v[202:205], 0
	v_mfma_f32_16x16x32_bf16 v[14:17], v[146:149], v[210:213], 0
	v_mfma_f32_16x16x32_bf16 v[10:13], v[162:165], v[210:213], 0
	v_mfma_f32_16x16x32_bf16 v[62:65], v[150:153], v[190:193], v[62:65]
	v_mfma_f32_16x16x32_bf16 v[58:61], v[166:169], v[190:193], v[58:61]
	v_mfma_f32_16x16x32_bf16 v[46:49], v[150:153], v[198:201], v[46:49]
	v_mfma_f32_16x16x32_bf16 v[42:45], v[166:169], v[198:201], v[42:45]
	v_mfma_f32_16x16x32_bf16 v[30:33], v[150:153], v[206:209], v[30:33]
	v_mfma_f32_16x16x32_bf16 v[26:29], v[166:169], v[206:209], v[26:29]
	v_mfma_f32_16x16x32_bf16 v[14:17], v[150:153], v[214:217], v[14:17]
	v_mfma_f32_16x16x32_bf16 v[10:13], v[166:169], v[214:217], v[10:13]
	s_setprio 0
	s_setprio 1
	v_mfma_f32_16x16x32_bf16 v[54:57], v[170:173], v[186:189], 0
	v_mfma_f32_16x16x32_bf16 v[50:53], v[178:181], v[186:189], 0
	v_mfma_f32_16x16x32_bf16 v[38:41], v[170:173], v[194:197], 0
	v_mfma_f32_16x16x32_bf16 v[34:37], v[178:181], v[194:197], 0
	v_mfma_f32_16x16x32_bf16 v[22:25], v[170:173], v[202:205], 0
	v_mfma_f32_16x16x32_bf16 v[18:21], v[178:181], v[202:205], 0
	v_mfma_f32_16x16x32_bf16 v[6:9], v[170:173], v[210:213], 0
	v_mfma_f32_16x16x32_bf16 v[2:5], v[178:181], v[210:213], 0
	v_mfma_f32_16x16x32_bf16 v[54:57], v[174:177], v[190:193], v[54:57]
	v_mfma_f32_16x16x32_bf16 v[50:53], v[182:185], v[190:193], v[50:53]
	v_mfma_f32_16x16x32_bf16 v[38:41], v[174:177], v[198:201], v[38:41]
	v_mfma_f32_16x16x32_bf16 v[34:37], v[182:185], v[198:201], v[34:37]
	v_mfma_f32_16x16x32_bf16 v[22:25], v[174:177], v[206:209], v[22:25]
	v_mfma_f32_16x16x32_bf16 v[18:21], v[182:185], v[206:209], v[18:21]
	v_mfma_f32_16x16x32_bf16 v[6:9], v[174:177], v[214:217], v[6:9]
	v_mfma_f32_16x16x32_bf16 v[2:5], v[182:185], v[214:217], v[2:5]
	s_setprio 0
	s_barrier
	s_add_i32 s75, 0, 0x18000
	v_add_u32_e32 v161, s75, v155
	s_add_i32 s76, 0, 0x1c000
	ds_read_b128 v[146:149], v161
	ds_read_b128 v[150:153], v161 offset:1024
	ds_read_b128 v[162:165], v161 offset:2048
	ds_read_b128 v[166:169], v161 offset:3072
	v_add_u32_e32 v161, s76, v155
	ds_read_b128 v[170:173], v161
	ds_read_b128 v[174:177], v161 offset:1024
	ds_read_b128 v[178:181], v161 offset:2048
	ds_read_b128 v[182:185], v161 offset:3072
	s_add_u32 s70, s70, 0x40000
	s_addc_u32 s71, s71, 0
	s_mov_b32 m0, s84
	v_lshl_add_u64 v[226:227], s[70:71], 0, v[130:131]
	ds_read_b128 v[186:189], v159 offset:32768
	ds_read_b128 v[190:193], v159 offset:33792
	ds_read_b128 v[194:197], v159 offset:34816
	ds_read_b128 v[198:201], v159 offset:35840
	ds_read_b128 v[202:205], v159 offset:36864
	ds_read_b128 v[206:209], v159 offset:37888
	ds_read_b128 v[210:213], v159 offset:38912
	ds_read_b128 v[214:217], v159 offset:39936
	global_load_lds_dwordx4 v[226:227], off
	v_lshl_add_u64 v[226:227], s[70:71], 0, v[134:135]
	s_mov_b32 m0, s85
	s_nop 0
	global_load_lds_dwordx4 v[226:227], off
	s_waitcnt vmcnt(8)
	s_waitcnt lgkmcnt(0)
	s_barrier
	s_setprio 1
	s_waitcnt lgkmcnt(0)
	v_mfma_f32_16x16x32_bf16 v[126:129], v[146:149], v[186:189], v[126:129]
	v_mfma_f32_16x16x32_bf16 v[122:125], v[162:165], v[186:189], v[122:125]
	v_mfma_f32_16x16x32_bf16 v[110:113], v[146:149], v[194:197], v[110:113]
	v_mfma_f32_16x16x32_bf16 v[106:109], v[162:165], v[194:197], v[106:109]
	v_mfma_f32_16x16x32_bf16 v[94:97], v[146:149], v[202:205], v[94:97]
	v_mfma_f32_16x16x32_bf16 v[90:93], v[162:165], v[202:205], v[90:93]
	v_mfma_f32_16x16x32_bf16 v[78:81], v[146:149], v[210:213], v[78:81]
	v_mfma_f32_16x16x32_bf16 v[74:77], v[162:165], v[210:213], v[74:77]
	v_mfma_f32_16x16x32_bf16 v[126:129], v[150:153], v[190:193], v[126:129]
	v_mfma_f32_16x16x32_bf16 v[122:125], v[166:169], v[190:193], v[122:125]
	v_mfma_f32_16x16x32_bf16 v[110:113], v[150:153], v[198:201], v[110:113]
	v_mfma_f32_16x16x32_bf16 v[106:109], v[166:169], v[198:201], v[106:109]
	v_mfma_f32_16x16x32_bf16 v[94:97], v[150:153], v[206:209], v[94:97]
	v_mfma_f32_16x16x32_bf16 v[90:93], v[166:169], v[206:209], v[90:93]
	v_mfma_f32_16x16x32_bf16 v[78:81], v[150:153], v[214:217], v[78:81]
	v_mfma_f32_16x16x32_bf16 v[74:77], v[166:169], v[214:217], v[74:77]
	s_setprio 0
	s_setprio 1
	v_mfma_f32_16x16x32_bf16 v[118:121], v[170:173], v[186:189], v[118:121]
	v_mfma_f32_16x16x32_bf16 v[114:117], v[178:181], v[186:189], v[114:117]
	v_mfma_f32_16x16x32_bf16 v[102:105], v[170:173], v[194:197], v[102:105]
	v_mfma_f32_16x16x32_bf16 v[98:101], v[178:181], v[194:197], v[98:101]
	v_mfma_f32_16x16x32_bf16 v[86:89], v[170:173], v[202:205], v[86:89]
	v_mfma_f32_16x16x32_bf16 v[82:85], v[178:181], v[202:205], v[82:85]
	v_mfma_f32_16x16x32_bf16 v[70:73], v[170:173], v[210:213], v[70:73]
	v_mfma_f32_16x16x32_bf16 v[66:69], v[178:181], v[210:213], v[66:69]
	v_mfma_f32_16x16x32_bf16 v[118:121], v[174:177], v[190:193], v[118:121]
	v_mfma_f32_16x16x32_bf16 v[114:117], v[182:185], v[190:193], v[114:117]
	v_mfma_f32_16x16x32_bf16 v[102:105], v[174:177], v[198:201], v[102:105]
	v_mfma_f32_16x16x32_bf16 v[98:101], v[182:185], v[198:201], v[98:101]
	v_mfma_f32_16x16x32_bf16 v[86:89], v[174:177], v[206:209], v[86:89]
	v_mfma_f32_16x16x32_bf16 v[82:85], v[182:185], v[206:209], v[82:85]
	v_mfma_f32_16x16x32_bf16 v[70:73], v[174:177], v[214:217], v[70:73]
	v_mfma_f32_16x16x32_bf16 v[66:69], v[182:185], v[214:217], v[66:69]
	s_setprio 0
	s_barrier
	s_add_i32 s70, s75, s81
	v_lshl_add_u64 v[218:219], v[218:219], 0, s[16:17]
	s_mov_b32 m0, s70
	ds_read_b128 v[186:189], v159 offset:49152
	ds_read_b128 v[190:193], v159 offset:50176
	ds_read_b128 v[194:197], v159 offset:51200
	ds_read_b128 v[198:201], v159 offset:52224
	ds_read_b128 v[202:205], v159 offset:53248
	ds_read_b128 v[206:209], v159 offset:54272
	ds_read_b128 v[210:213], v159 offset:55296
	ds_read_b128 v[214:217], v159 offset:56320
	global_load_lds_dwordx4 v[218:219], off
	s_add_i32 m0, s70, 0x2000
	s_add_u32 s56, s56, 0x40080
	v_lshl_add_u64 v[218:219], v[220:221], 0, s[16:17]
	s_addc_u32 s57, s57, 0
	s_add_i32 s70, s76, s81
	global_load_lds_dwordx4 v[218:219], off
	v_lshl_add_u64 v[218:219], s[56:57], 0, v[132:133]
	s_mov_b32 m0, s70
	s_nop 0
	global_load_lds_dwordx4 v[218:219], off
	v_lshl_add_u64 v[218:219], s[56:57], 0, v[136:137]
	s_add_i32 m0, s70, 0x2000
	s_nop 0
	global_load_lds_dwordx4 v[218:219], off
	v_lshl_add_u64 v[218:219], v[222:223], 0, s[16:17]
	s_mov_b32 m0, s87
	s_nop 0
	global_load_lds_dwordx4 v[218:219], off
	v_lshl_add_u64 v[218:219], v[224:225], 0, s[16:17]
	s_mov_b32 m0, s88
	s_nop 0
	global_load_lds_dwordx4 v[218:219], off
	s_waitcnt vmcnt(8)
	s_waitcnt lgkmcnt(0)
	s_barrier
	s_setprio 1
	s_waitcnt lgkmcnt(0)
	v_mfma_f32_16x16x32_bf16 v[62:65], v[146:149], v[186:189], v[62:65]
	v_mfma_f32_16x16x32_bf16 v[58:61], v[162:165], v[186:189], v[58:61]
	v_mfma_f32_16x16x32_bf16 v[46:49], v[146:149], v[194:197], v[46:49]
	v_mfma_f32_16x16x32_bf16 v[42:45], v[162:165], v[194:197], v[42:45]
	v_mfma_f32_16x16x32_bf16 v[30:33], v[146:149], v[202:205], v[30:33]
	v_mfma_f32_16x16x32_bf16 v[26:29], v[162:165], v[202:205], v[26:29]
	v_mfma_f32_16x16x32_bf16 v[14:17], v[146:149], v[210:213], v[14:17]
	v_mfma_f32_16x16x32_bf16 v[10:13], v[162:165], v[210:213], v[10:13]
	v_mfma_f32_16x16x32_bf16 v[62:65], v[150:153], v[190:193], v[62:65]
	v_mfma_f32_16x16x32_bf16 v[58:61], v[166:169], v[190:193], v[58:61]
	v_mfma_f32_16x16x32_bf16 v[46:49], v[150:153], v[198:201], v[46:49]
	v_mfma_f32_16x16x32_bf16 v[42:45], v[166:169], v[198:201], v[42:45]
	v_mfma_f32_16x16x32_bf16 v[30:33], v[150:153], v[206:209], v[30:33]
	v_mfma_f32_16x16x32_bf16 v[26:29], v[166:169], v[206:209], v[26:29]
	v_mfma_f32_16x16x32_bf16 v[14:17], v[150:153], v[214:217], v[14:17]
	v_mfma_f32_16x16x32_bf16 v[10:13], v[166:169], v[214:217], v[10:13]
	s_setprio 0
	s_setprio 1
	v_mfma_f32_16x16x32_bf16 v[54:57], v[170:173], v[186:189], v[54:57]
	v_mfma_f32_16x16x32_bf16 v[50:53], v[178:181], v[186:189], v[50:53]
	v_mfma_f32_16x16x32_bf16 v[38:41], v[170:173], v[194:197], v[38:41]
	v_mfma_f32_16x16x32_bf16 v[34:37], v[178:181], v[194:197], v[34:37]
	v_mfma_f32_16x16x32_bf16 v[22:25], v[170:173], v[202:205], v[22:25]
	v_mfma_f32_16x16x32_bf16 v[18:21], v[178:181], v[202:205], v[18:21]
	v_mfma_f32_16x16x32_bf16 v[6:9], v[170:173], v[210:213], v[6:9]
	v_mfma_f32_16x16x32_bf16 v[2:5], v[178:181], v[210:213], v[2:5]
	v_mfma_f32_16x16x32_bf16 v[54:57], v[174:177], v[190:193], v[54:57]
	v_mfma_f32_16x16x32_bf16 v[50:53], v[182:185], v[190:193], v[50:53]
	v_mfma_f32_16x16x32_bf16 v[38:41], v[174:177], v[198:201], v[38:41]
	v_mfma_f32_16x16x32_bf16 v[34:37], v[182:185], v[198:201], v[34:37]
	v_mfma_f32_16x16x32_bf16 v[22:25], v[174:177], v[206:209], v[22:25]
	v_mfma_f32_16x16x32_bf16 v[18:21], v[182:185], v[206:209], v[18:21]
	v_mfma_f32_16x16x32_bf16 v[6:9], v[174:177], v[214:217], v[6:9]
	v_mfma_f32_16x16x32_bf16 v[2:5], v[182:185], v[214:217], v[2:5]
	s_setprio 0
	s_barrier
	s_add_i32 s74, s74, 2
	s_add_u32 s54, s54, 0x100
	s_addc_u32 s55, s55, 0
	s_add_u32 s72, s72, 0x100
	s_addc_u32 s73, s73, 0
	s_cmp_gt_u32 s74, 13
